# attention: softmax denominators accumulated directly in the loop-carried registers (two copies per tile removed)
# baseline (speedup 1.0000x reference)
.LBB0_688:
	s_waitcnt lgkmcnt(0)
	v_max3_f32 v133, v193, v132, v133
	v_sub_f32_e32 v18, v18, v133
	v_exp_f32_e32 v134, v18
	v_sub_f32_e32 v19, v19, v133
	v_exp_f32_e32 v19, v19
	v_sub_f32_e32 v20, v20, v133
	v_exp_f32_e32 v20, v20
	v_sub_f32_e32 v21, v21, v133
	v_exp_f32_e32 v21, v21
	v_sub_f32_e32 v22, v22, v133
	v_add_f32_e32 v132, 0, v134
	v_exp_f32_e32 v135, v22
	v_sub_f32_e32 v23, v23, v133
	v_add_f32_e32 v22, v19, v132
	v_exp_f32_e32 v136, v23
	v_sub_f32_e32 v23, v24, v133
	v_add_f32_e32 v22, v20, v22
	v_exp_f32_e32 v137, v23
	v_sub_f32_e32 v23, v25, v133
	v_add_f32_e32 v22, v21, v22
	v_exp_f32_e32 v138, v23
	v_sub_f32_e32 v23, v26, v133
	v_add_f32_e32 v22, v135, v22
	v_exp_f32_e32 v139, v23
	v_sub_f32_e32 v23, v27, v133
	v_add_f32_e32 v22, v136, v22
	v_exp_f32_e32 v140, v23
	v_sub_f32_e32 v23, v28, v133
	v_add_f32_e32 v22, v137, v22
	v_exp_f32_e32 v141, v23
	v_sub_f32_e32 v23, v29, v133
	v_add_f32_e32 v22, v138, v22
	v_exp_f32_e32 v142, v23
	v_sub_f32_e32 v23, v30, v133
	v_add_f32_e32 v22, v139, v22
	v_exp_f32_e32 v143, v23
	v_sub_f32_e32 v23, v31, v133
	v_add_f32_e32 v22, v140, v22
	v_exp_f32_e32 v144, v23
	v_sub_f32_e32 v23, v32, v133
	v_sub_f32_e32 v18, v193, v133
	v_add_f32_e32 v22, v141, v22
	v_exp_f32_e32 v145, v23
	v_sub_f32_e32 v23, v33, v133
	v_add_f32_e32 v22, v142, v22
	v_exp_f32_e32 v146, v23
	v_exp_f32_e32 v18, v18
	v_add_f32_e32 v22, v143, v22
	v_add_f32_e32 v22, v144, v22
	v_add_f32_e32 v22, v145, v22
	v_add_f32_e32 v132, v146, v22
	v_mul_f32_e32 v22, v100, v18
	v_mul_f32_e32 v23, v101, v18
	v_cvt_pk_f16_f32 v100, v134, v19
	v_max3_f32 v134, v191, v194, v195
	v_sub_f32_e32 v2, v2, v134
	v_mul_f32_e32 v30, v108, v18
	v_mul_f32_e32 v31, v109, v18
	v_exp_f32_e32 v108, v2
	v_sub_f32_e32 v3, v3, v134
	v_exp_f32_e32 v3, v3
	v_sub_f32_e32 v4, v4, v134
	v_mul_f32_e32 v32, v110, v18
	v_mul_f32_e32 v33, v111, v18
	v_exp_f32_e32 v110, v4
	v_sub_f32_e32 v4, v5, v134
	v_exp_f32_e32 v111, v4
	v_sub_f32_e32 v4, v6, v134
	v_mul_f32_e32 v26, v128, v18
	v_mul_f32_e32 v27, v129, v18
	v_add_f32_e32 v109, 0, v108
	v_exp_f32_e32 v128, v4
	v_sub_f32_e32 v5, v7, v134
	v_add_f32_e32 v4, v3, v109
	v_exp_f32_e32 v109, v5
	v_sub_f32_e32 v5, v8, v134
	v_add_f32_e32 v4, v110, v4
	v_exp_f32_e32 v129, v5
	v_sub_f32_e32 v5, v9, v134
	v_mul_f32_e32 v28, v130, v18
	v_mul_f32_e32 v29, v131, v18
	v_add_f32_e32 v4, v111, v4
	v_exp_f32_e32 v130, v5
	v_sub_f32_e32 v5, v10, v134
	v_add_f32_e32 v4, v128, v4
	v_exp_f32_e32 v131, v5
	v_sub_f32_e32 v5, v11, v134
	v_mul_f32_e32 v24, v102, v18
	v_mul_f32_e32 v25, v103, v18
	v_cvt_pk_f16_f32 v102, v135, v136
	v_add_f32_e32 v4, v109, v4
	v_exp_f32_e32 v135, v5
	v_sub_f32_e32 v5, v12, v134
	v_add_f32_e32 v4, v129, v4
	v_exp_f32_e32 v136, v5
	v_sub_f32_e32 v5, v13, v134
	v_cvt_pk_f16_f32 v103, v137, v138
	v_add_f32_e32 v4, v130, v4
	v_exp_f32_e32 v137, v5
	v_sub_f32_e32 v5, v14, v134
	v_add_f32_e32 v4, v131, v4
	v_exp_f32_e32 v138, v5
	v_sub_f32_e32 v5, v15, v134
	v_fma_f32 v192, v192, v18, v132
	v_mul_f32_e32 v126, v126, v18
	v_mul_f32_e32 v127, v127, v18
	v_mul_f32_e32 v124, v124, v18
	v_mul_f32_e32 v125, v125, v18
	v_mul_f32_e32 v122, v122, v18
	v_mul_f32_e32 v123, v123, v18
	v_mul_f32_e32 v120, v120, v18
	v_mul_f32_e32 v121, v121, v18
	v_mul_f32_e32 v118, v118, v18
	v_mul_f32_e32 v119, v119, v18
	v_mul_f32_e32 v116, v116, v18
	v_mul_f32_e32 v117, v117, v18
	v_mul_f32_e32 v114, v114, v18
	v_mul_f32_e32 v115, v115, v18
	v_mul_f32_e32 v112, v112, v18
	v_mul_f32_e32 v113, v113, v18
	v_mul_f32_e32 v106, v106, v18
	v_mul_f32_e32 v107, v107, v18
	v_mul_f32_e32 v104, v104, v18
	v_mul_f32_e32 v105, v105, v18
	v_cvt_pk_f16_f32 v18, v139, v140
	v_add_f32_e32 v4, v135, v4
	v_exp_f32_e32 v139, v5
	v_sub_f32_e32 v5, v16, v134
	v_add_f32_e32 v4, v136, v4
	v_exp_f32_e32 v140, v5
	v_sub_f32_e32 v5, v17, v134
	v_sub_f32_e32 v2, v191, v134
	v_add_f32_e32 v4, v137, v4
	v_exp_f32_e32 v17, v5
	v_add_f32_e32 v4, v138, v4
	v_exp_f32_e32 v16, v2
	v_add_f32_e32 v2, v139, v4
	v_add_f32_e32 v2, v140, v2
	v_add_f32_e32 v2, v17, v2
	v_cvt_pk_f16_f32 v101, v20, v21
	v_fma_f32 v190, v190, v16, v2
	v_mul_f32_e32 v10, v78, v16
	v_mul_f32_e32 v11, v79, v16
	v_mul_f32_e32 v8, v76, v16
	v_mul_f32_e32 v9, v77, v16
	v_mul_f32_e32 v14, v70, v16
	v_mul_f32_e32 v15, v71, v16
	v_mul_f32_e32 v12, v68, v16
	v_mul_f32_e32 v13, v69, v16
	v_mul_f32_e32 v66, v66, v16
	v_mul_f32_e32 v67, v67, v16
	v_mul_f32_e32 v64, v64, v16
	v_mul_f32_e32 v65, v65, v16
	v_mul_f32_e32 v62, v62, v16
	v_mul_f32_e32 v63, v63, v16
	v_mul_f32_e32 v60, v60, v16
	v_mul_f32_e32 v61, v61, v16
	v_mul_f32_e32 v58, v58, v16
	v_mul_f32_e32 v59, v59, v16
	v_mul_f32_e32 v56, v56, v16
	v_mul_f32_e32 v57, v57, v16
	v_mul_f32_e32 v54, v54, v16
	v_mul_f32_e32 v55, v55, v16
	v_mul_f32_e32 v52, v52, v16
	v_mul_f32_e32 v53, v53, v16
	v_mul_f32_e32 v70, v98, v16
	v_mul_f32_e32 v71, v99, v16
	v_mul_f32_e32 v68, v96, v16
	v_mul_f32_e32 v69, v97, v16
	v_cvt_pk_f16_f32 v76, v108, v3
	v_cvt_pk_f16_f32 v77, v110, v111
	v_cvt_pk_f16_f32 v78, v128, v109
	v_cvt_pk_f16_f32 v79, v129, v130
	v_cvt_pk_f16_f32 v96, v131, v135
	v_cvt_pk_f16_f32 v97, v136, v137
	v_cvt_pk_f16_f32 v98, v138, v139
	v_cvt_pk_f16_f32 v99, v140, v17
	v_cvt_pk_f16_f32 v19, v141, v142
	v_cvt_pk_f16_f32 v20, v143, v144
	v_cvt_pk_f16_f32 v21, v145, v146
	v_mul_f32_e32 v6, v90, v16
	v_mul_f32_e32 v7, v91, v16
	v_mul_f32_e32 v4, v88, v16
	v_mul_f32_e32 v5, v89, v16
	s_mul_i32 s2, s50, 0x4800
	v_add_u32_e32 v3, s2, v227
	ds_read_b64_tr_b16 v[140:141], v3 offset:34816
	ds_read_b64_tr_b16 v[142:143], v3 offset:39424
	ds_read_b64_tr_b16 v[144:145], v3 offset:34848
	ds_read_b64_tr_b16 v[146:147], v3 offset:39456
	ds_read_b64_tr_b16 v[246:247], v3 offset:34880
	ds_read_b64_tr_b16 v[248:249], v3 offset:39488
	ds_read_b64_tr_b16 v[250:251], v3 offset:34912
	ds_read_b64_tr_b16 v[252:253], v3 offset:39520
	s_waitcnt lgkmcnt(6)
	v_mfma_f32_16x16x32_f16 v[4:7], v[140:143], v[76:79], v[4:7]
	v_mfma_f32_16x16x32_f16 v[108:111], v[140:143], v[100:103], v[124:127]
	ds_read_b64_tr_b16 v[140:141], v3 offset:34944
	ds_read_b64_tr_b16 v[142:143], v3 offset:39552
	s_waitcnt lgkmcnt(6)
	v_mfma_f32_16x16x32_f16 v[120:123], v[144:147], v[100:103], v[120:123]
	v_mfma_f32_16x16x32_f16 v[8:11], v[144:147], v[76:79], v[8:11]
	ds_read_b64_tr_b16 v[144:145], v3 offset:34976
	ds_read_b64_tr_b16 v[146:147], v3 offset:39584
	s_waitcnt lgkmcnt(6)
	v_mfma_f32_16x16x32_f16 v[12:15], v[246:249], v[76:79], v[12:15]
	v_mfma_f32_16x16x32_f16 v[116:119], v[246:249], v[100:103], v[116:119]
	ds_read_b64_tr_b16 v[246:247], v3 offset:35008
	ds_read_b64_tr_b16 v[248:249], v3 offset:39616
	s_waitcnt lgkmcnt(6)
	v_mfma_f32_16x16x32_f16 v[64:67], v[250:253], v[76:79], v[64:67]
	v_mfma_f32_16x16x32_f16 v[112:115], v[250:253], v[100:103], v[112:115]
	ds_read_b64_tr_b16 v[250:251], v3 offset:35040
	ds_read_b64_tr_b16 v[252:253], v3 offset:39648
	s_waitcnt lgkmcnt(6)
	v_mfma_f32_16x16x32_f16 v[60:63], v[140:143], v[76:79], v[60:63]
	v_mfma_f32_16x16x32_f16 v[30:33], v[140:143], v[100:103], v[30:33]
	ds_read_b64_tr_b16 v[140:141], v3 offset:44032
	ds_read_b64_tr_b16 v[142:143], v3 offset:48640
	s_waitcnt lgkmcnt(6)
	v_mfma_f32_16x16x32_f16 v[56:59], v[144:147], v[76:79], v[56:59]
	v_mfma_f32_16x16x32_f16 v[104:107], v[144:147], v[100:103], v[104:107]
	ds_read_b64_tr_b16 v[144:145], v3 offset:44064
	ds_read_b64_tr_b16 v[146:147], v3 offset:48672
	s_waitcnt lgkmcnt(6)
	v_mfma_f32_16x16x32_f16 v[52:55], v[246:249], v[76:79], v[52:55]
	v_mfma_f32_16x16x32_f16 v[22:25], v[246:249], v[100:103], v[22:25]
	ds_read_b64_tr_b16 v[246:247], v3 offset:44096
	ds_read_b64_tr_b16 v[248:249], v3 offset:48704
	s_waitcnt lgkmcnt(6)
	v_mfma_f32_16x16x32_f16 v[128:131], v[250:253], v[76:79], v[68:71]
	v_mfma_f32_16x16x32_f16 v[26:29], v[250:253], v[100:103], v[26:29]
	ds_read_b64_tr_b16 v[250:251], v3 offset:44128
	ds_read_b64_tr_b16 v[252:253], v3 offset:48736
	s_waitcnt lgkmcnt(6)
	v_mfma_f32_16x16x32_f16 v[88:91], v[140:143], v[96:99], v[4:7]
	v_mfma_f32_16x16x32_f16 v[124:127], v[140:143], v[18:21], v[108:111]
	ds_read_b64_tr_b16 v[140:141], v3 offset:44160
	ds_read_b64_tr_b16 v[142:143], v3 offset:48768
	s_waitcnt lgkmcnt(6)
	v_mfma_f32_16x16x32_f16 v[76:79], v[144:147], v[96:99], v[8:11]
	v_mfma_f32_16x16x32_f16 v[120:123], v[144:147], v[18:21], v[120:123]
	ds_read_b64_tr_b16 v[144:145], v3 offset:44192
	ds_read_b64_tr_b16 v[146:147], v3 offset:48800
	s_waitcnt lgkmcnt(6)
	v_mfma_f32_16x16x32_f16 v[68:71], v[246:249], v[96:99], v[12:15]
	v_mfma_f32_16x16x32_f16 v[116:119], v[246:249], v[18:21], v[116:119]
	ds_read_b64_tr_b16 v[246:247], v3 offset:44224
	ds_read_b64_tr_b16 v[248:249], v3 offset:48832
	s_waitcnt lgkmcnt(6)
	v_mfma_f32_16x16x32_f16 v[64:67], v[250:253], v[96:99], v[64:67]
	v_mfma_f32_16x16x32_f16 v[112:115], v[250:253], v[18:21], v[112:115]
	ds_read_b64_tr_b16 v[250:251], v3 offset:44256
	ds_read_b64_tr_b16 v[252:253], v3 offset:48864
	s_waitcnt lgkmcnt(6)
	v_mfma_f32_16x16x32_f16 v[60:63], v[140:143], v[96:99], v[60:63]
	v_mfma_f32_16x16x32_f16 v[108:111], v[140:143], v[18:21], v[30:33]
	s_waitcnt lgkmcnt(4)
	v_mfma_f32_16x16x32_f16 v[56:59], v[144:147], v[96:99], v[56:59]
	v_mfma_f32_16x16x32_f16 v[104:107], v[144:147], v[18:21], v[104:107]
	s_waitcnt lgkmcnt(2)
	v_mfma_f32_16x16x32_f16 v[52:55], v[246:249], v[96:99], v[52:55]
	v_mfma_f32_16x16x32_f16 v[100:103], v[246:249], v[18:21], v[22:25]
	s_waitcnt lgkmcnt(0)
	v_mfma_f32_16x16x32_f16 v[96:99], v[250:253], v[96:99], v[128:131]
	v_mfma_f32_16x16x32_f16 v[128:131], v[250:253], v[18:21], v[26:29]
	s_add_i32 s49, s49, 1
	s_add_i32 s24, s24, 64
	s_add_i32 s2, s31, s49
	v_lshl_add_u64 v[172:173], v[172:173], 0, s[20:21]
	v_lshl_add_u64 v[170:171], v[170:171], 0, s[20:21]
	s_cmp_eq_u32 s2, 2
	v_subrev_u32_e32 v167, 64, v167
	s_barrier
	s_cbranch_scc1 .LBB0_691
	v_mov_b32_e32 v193, v133
	v_mov_b32_e32 v191, v134
	s_branch .LBB0_677

.LBB0_691:
	ds_bpermute_b32 v3, v35, v190
	s_mov_b32 s40, 0
	s_waitcnt lgkmcnt(0)
	v_add_f32_e32 v2, v190, v3
	ds_bpermute_b32 v3, v149, v2
	s_waitcnt lgkmcnt(0)
	v_add_f32_e32 v2, v2, v3
	ds_bpermute_b32 v3, v35, v192
	s_waitcnt lgkmcnt(0)
	v_add_f32_e32 v3, v192, v3
	ds_bpermute_b32 v4, v149, v3
	s_waitcnt lgkmcnt(0)
	v_add_f32_e32 v3, v3, v4
	v_div_scale_f32 v4, s[2:3], v2, v2, 1.0
	v_rcp_f32_e32 v5, v4
	s_nop 0
	v_fma_f32 v6, -v4, v5, 1.0
	v_fmac_f32_e32 v5, v6, v5
	v_div_scale_f32 v6, vcc, 1.0, v2, 1.0
	v_mul_f32_e32 v7, v6, v5
	v_fma_f32 v8, -v4, v7, v6
	v_fmac_f32_e32 v7, v8, v5
	v_fma_f32 v4, -v4, v7, v6
	v_div_fmas_f32 v4, v4, v5, v7
	v_div_fixup_f32 v12, v4, v2, 1.0
	v_div_scale_f32 v2, s[2:3], v3, v3, v181
	v_rcp_f32_e32 v4, v2
	s_nop 0
	v_fma_f32 v5, -v2, v4, 1.0
	v_fmac_f32_e32 v4, v5, v4
	v_div_scale_f32 v5, vcc, v181, v3, v181
	v_mul_f32_e32 v6, v5, v4
	v_fma_f32 v7, -v2, v6, v5
	v_fmac_f32_e32 v6, v7, v4
	v_fma_f32 v2, -v2, v6, v5
	v_div_fmas_f32 v2, v2, v4, v6
	v_div_fixup_f32 v14, v2, v3, v181
	v_pk_mul_f32 v[8:9], v[126:127], v[14:15] op_sel_hi:[1,0]
	v_pk_mul_f32 v[24:25], v[124:125], v[14:15] op_sel_hi:[1,0]
	v_pk_fma_f32 v[20:21], v[90:91], v[12:13], v[8:9] op_sel_hi:[1,0,1] neg_lo:[0,0,1] neg_hi:[0,0,1]
	global_load_dwordx4 v[8:11], v[160:161], off
	global_load_dwordx4 v[80:83], v[160:161], off offset:64
	global_load_dwordx4 v[84:87], v[160:161], off offset:128
	global_load_dwordx4 v[92:95], v[160:161], off offset:192
	global_load_dwordx4 v[228:231], v[160:161], off offset:256
	global_load_dwordx4 v[232:235], v[160:161], off offset:320
	global_load_dwordx4 v[236:239], v[160:161], off offset:384
	global_load_dwordx4 v[240:243], v[160:161], off offset:448
	v_pk_fma_f32 v[24:25], v[88:89], v[12:13], v[24:25] op_sel_hi:[1,0,1] neg_lo:[0,0,1] neg_hi:[0,0,1]
	v_pk_mul_f32 v[22:23], v[20:21], v[20:21]
	v_pk_mul_f32 v[26:27], v[24:25], v[24:25]
	v_pk_mul_f32 v[32:33], v[120:121], v[14:15] op_sel_hi:[1,0]
	v_add_f32_e32 v26, v26, v27
	v_pk_fma_f32 v[32:33], v[76:77], v[12:13], v[32:33] op_sel_hi:[1,0,1] neg_lo:[0,0,1] neg_hi:[0,0,1]
	v_add_f32_e32 v22, v22, v26
	v_pk_mul_f32 v[28:29], v[122:123], v[14:15] op_sel_hi:[1,0]
	v_pk_mul_f32 v[36:37], v[32:33], v[32:33]
	v_add_f32_e32 v22, v23, v22
	v_pk_fma_f32 v[28:29], v[78:79], v[12:13], v[28:29] op_sel_hi:[1,0,1] neg_lo:[0,0,1] neg_hi:[0,0,1]
	v_add_f32_e32 v22, v36, v22
	v_pk_mul_f32 v[30:31], v[28:29], v[28:29]
	v_pk_mul_f32 v[42:43], v[116:117], v[14:15] op_sel_hi:[1,0]
	v_add_f32_e32 v22, v37, v22
	v_pk_fma_f32 v[42:43], v[68:69], v[12:13], v[42:43] op_sel_hi:[1,0,1] neg_lo:[0,0,1] neg_hi:[0,0,1]
	v_add_f32_e32 v22, v30, v22
	v_pk_mul_f32 v[38:39], v[118:119], v[14:15] op_sel_hi:[1,0]
	v_pk_mul_f32 v[44:45], v[42:43], v[42:43]
	v_add_f32_e32 v22, v31, v22
	v_pk_fma_f32 v[38:39], v[70:71], v[12:13], v[38:39] op_sel_hi:[1,0,1] neg_lo:[0,0,1] neg_hi:[0,0,1]
	v_add_f32_e32 v22, v44, v22
	v_pk_mul_f32 v[40:41], v[38:39], v[38:39]
	v_pk_mul_f32 v[50:51], v[112:113], v[14:15] op_sel_hi:[1,0]
	v_add_f32_e32 v22, v45, v22
	v_pk_fma_f32 v[50:51], v[64:65], v[12:13], v[50:51] op_sel_hi:[1,0,1] neg_lo:[0,0,1] neg_hi:[0,0,1]
	v_add_f32_e32 v22, v40, v22
	v_pk_mul_f32 v[46:47], v[114:115], v[14:15] op_sel_hi:[1,0]
	v_pk_mul_f32 v[64:65], v[50:51], v[50:51]
	v_add_f32_e32 v22, v41, v22
	v_pk_fma_f32 v[46:47], v[66:67], v[12:13], v[46:47] op_sel_hi:[1,0,1] neg_lo:[0,0,1] neg_hi:[0,0,1]
	v_add_f32_e32 v22, v64, v22
	v_pk_mul_f32 v[48:49], v[46:47], v[46:47]
	v_pk_mul_f32 v[68:69], v[108:109], v[14:15] op_sel_hi:[1,0]
	v_add_f32_e32 v22, v65, v22
	v_pk_fma_f32 v[60:61], v[60:61], v[12:13], v[68:69] op_sel_hi:[1,0,1] neg_lo:[0,0,1] neg_hi:[0,0,1]
	v_add_f32_e32 v22, v48, v22
	v_pk_mul_f32 v[66:67], v[110:111], v[14:15] op_sel_hi:[1,0]
	v_pk_mul_f32 v[68:69], v[60:61], v[60:61]
	v_add_f32_e32 v22, v49, v22
	v_pk_fma_f32 v[62:63], v[62:63], v[12:13], v[66:67] op_sel_hi:[1,0,1] neg_lo:[0,0,1] neg_hi:[0,0,1]
	v_add_f32_e32 v22, v68, v22
	v_pk_mul_f32 v[66:67], v[62:63], v[62:63]
	s_waitcnt vmcnt(4)
	v_pk_mul_f32 v[72:73], v[104:105], v[14:15] op_sel_hi:[1,0]
	v_add_f32_e32 v22, v69, v22
	v_pk_fma_f32 v[56:57], v[56:57], v[12:13], v[72:73] op_sel_hi:[1,0,1] neg_lo:[0,0,1] neg_hi:[0,0,1]
	v_add_f32_e32 v22, v66, v22
	v_pk_mul_f32 v[70:71], v[106:107], v[14:15] op_sel_hi:[1,0]
	v_pk_mul_f32 v[72:73], v[56:57], v[56:57]
	v_add_f32_e32 v22, v67, v22
	v_pk_mul_f32 v[2:3], v[128:129], v[14:15] op_sel_hi:[1,0]
	v_pk_fma_f32 v[58:59], v[58:59], v[12:13], v[70:71] op_sel_hi:[1,0,1] neg_lo:[0,0,1] neg_hi:[0,0,1]
	v_add_f32_e32 v22, v72, v22
	v_pk_fma_f32 v[6:7], v[96:97], v[12:13], v[2:3] op_sel_hi:[1,0,1] neg_lo:[0,0,1] neg_hi:[0,0,1]
	v_pk_mul_f32 v[2:3], v[130:131], v[14:15] op_sel_hi:[1,0]
	v_pk_mul_f32 v[70:71], v[58:59], v[58:59]
	v_pk_mul_f32 v[74:75], v[102:103], v[14:15] op_sel_hi:[1,0]
	v_pk_mul_f32 v[14:15], v[100:101], v[14:15] op_sel_hi:[1,0]
	v_add_f32_e32 v22, v73, v22
	v_pk_fma_f32 v[4:5], v[98:99], v[12:13], v[2:3] op_sel_hi:[1,0,1] neg_lo:[0,0,1] neg_hi:[0,0,1]
	v_pk_fma_f32 v[54:55], v[54:55], v[12:13], v[74:75] op_sel_hi:[1,0,1] neg_lo:[0,0,1] neg_hi:[0,0,1]
	v_pk_fma_f32 v[12:13], v[52:53], v[12:13], v[14:15] op_sel_hi:[1,0,1] neg_lo:[0,0,1] neg_hi:[0,0,1]
	v_add_f32_e32 v22, v70, v22
	v_pk_mul_f32 v[14:15], v[12:13], v[12:13]
	v_add_f32_e32 v22, v71, v22
	v_add_f32_e32 v14, v14, v22
	v_pk_mul_f32 v[74:75], v[54:55], v[54:55]
	v_add_f32_e32 v14, v15, v14
	v_add_f32_e32 v14, v74, v14
	v_pk_mul_f32 v[16:17], v[6:7], v[6:7]
	v_add_f32_e32 v14, v75, v14
	v_add_f32_e32 v14, v16, v14
	v_pk_mul_f32 v[18:19], v[4:5], v[4:5]
	v_add_f32_e32 v14, v17, v14
	v_add_f32_e32 v14, v18, v14
	v_add_f32_e32 v14, v19, v14
	ds_bpermute_b32 v15, v35, v14
	v_lshlrev_b32_e32 v2, 1, v156
	v_mov_b32_e32 v3, v34
	v_lshl_add_u64 v[2:3], v[168:169], 0, v[2:3]
	s_waitcnt lgkmcnt(0)
	v_add_f32_e32 v14, v14, v15
	ds_bpermute_b32 v15, v149, v14
	s_waitcnt lgkmcnt(0)
	v_add_f32_e32 v14, v14, v15
	v_fmamk_f32 v14, v14, 0x3c000000, v212
	v_cmp_gt_f32_e32 vcc, s27, v14
	v_mul_f32_e32 v15, 0x4b800000, v14
	s_nop 0
	v_cndmask_b32_e32 v14, v14, v15, vcc
	v_rsq_f32_e32 v14, v14
	s_nop 0
	v_mul_f32_e32 v15, 0x45800000, v14
	v_cndmask_b32_e32 v14, v14, v15, vcc
	v_mul_f32_e32 v14, v179, v14
	v_pk_mul_f32 v[16:17], v[24:25], v[14:15] op_sel_hi:[1,0]
	v_pk_mul_f32 v[12:13], v[12:13], v[14:15] op_sel_hi:[1,0]
	s_waitcnt vmcnt(0)
	v_pk_mul_f32 v[8:9], v[8:9], v[16:17]
	v_pk_mul_f32 v[16:17], v[20:21], v[14:15] op_sel_hi:[1,0]
	v_cvt_pk_f16_f32 v8, v8, v9
	v_pk_mul_f32 v[10:11], v[10:11], v[16:17]
	v_pk_mul_f32 v[16:17], v[32:33], v[14:15] op_sel_hi:[1,0]
	v_cvt_pk_f16_f32 v9, v10, v11
	global_store_dwordx2 v[2:3], v[8:9], off offset:1024
	v_pk_mul_f32 v[6:7], v[6:7], v[14:15] op_sel_hi:[1,0]
	v_pk_mul_f32 v[4:5], v[4:5], v[14:15] op_sel_hi:[1,0]
	v_pk_mul_f32 v[8:9], v[80:81], v[16:17]
	v_pk_mul_f32 v[16:17], v[28:29], v[14:15] op_sel_hi:[1,0]
	v_cvt_pk_f16_f32 v8, v8, v9
	v_pk_mul_f32 v[10:11], v[82:83], v[16:17]
	v_pk_mul_f32 v[16:17], v[42:43], v[14:15] op_sel_hi:[1,0]
	v_cvt_pk_f16_f32 v9, v10, v11
	global_store_dwordx2 v[2:3], v[8:9], off offset:1056
	v_pk_mul_f32 v[8:9], v[84:85], v[16:17]
	v_pk_mul_f32 v[16:17], v[38:39], v[14:15] op_sel_hi:[1,0]
	v_cvt_pk_f16_f32 v8, v8, v9
	v_pk_mul_f32 v[10:11], v[86:87], v[16:17]
	v_pk_mul_f32 v[16:17], v[50:51], v[14:15] op_sel_hi:[1,0]
	v_cvt_pk_f16_f32 v9, v10, v11
	global_store_dwordx2 v[2:3], v[8:9], off offset:1088
	v_pk_mul_f32 v[8:9], v[92:93], v[16:17]
	v_pk_mul_f32 v[16:17], v[46:47], v[14:15] op_sel_hi:[1,0]
	v_cvt_pk_f16_f32 v8, v8, v9
	v_pk_mul_f32 v[10:11], v[94:95], v[16:17]
	v_pk_mul_f32 v[16:17], v[60:61], v[14:15] op_sel_hi:[1,0]
	v_cvt_pk_f16_f32 v9, v10, v11
	global_store_dwordx2 v[2:3], v[8:9], off offset:1120
	v_pk_mul_f32 v[8:9], v[228:229], v[16:17]
	v_pk_mul_f32 v[16:17], v[62:63], v[14:15] op_sel_hi:[1,0]
	v_cvt_pk_f16_f32 v8, v8, v9
	v_pk_mul_f32 v[10:11], v[230:231], v[16:17]
	v_pk_mul_f32 v[16:17], v[56:57], v[14:15] op_sel_hi:[1,0]
	v_cvt_pk_f16_f32 v9, v10, v11
	global_store_dwordx2 v[2:3], v[8:9], off offset:1152
	v_pk_mul_f32 v[8:9], v[232:233], v[16:17]
	v_pk_mul_f32 v[16:17], v[58:59], v[14:15] op_sel_hi:[1,0]
	v_cvt_pk_f16_f32 v8, v8, v9
	v_pk_mul_f32 v[10:11], v[234:235], v[16:17]
	s_nop 0
	v_cvt_pk_f16_f32 v9, v10, v11
	global_store_dwordx2 v[2:3], v[8:9], off offset:1184
	v_pk_mul_f32 v[8:9], v[236:237], v[12:13]
	v_pk_mul_f32 v[12:13], v[54:55], v[14:15] op_sel_hi:[1,0]
	v_cvt_pk_f16_f32 v8, v8, v9
	v_pk_mul_f32 v[10:11], v[238:239], v[12:13]
	s_nop 0
	v_cvt_pk_f16_f32 v9, v10, v11
	global_store_dwordx2 v[2:3], v[8:9], off offset:1216
	v_pk_mul_f32 v[6:7], v[240:241], v[6:7]
	v_pk_mul_f32 v[4:5], v[242:243], v[4:5]
	v_cvt_pk_f16_f32 v6, v6, v7
	v_cvt_pk_f16_f32 v7, v4, v5
	global_store_dwordx2 v[2:3], v[6:7], off offset:1248
